# v17: v9 + P0 odd workgroups run the row norms before the weight transposes (even: transposes first) so the HBM-bound and latency-bound halves overlap
# speedup vs baseline: 1.0123x; 1.0035x over previous
; DI void tr_weight(const float* W, bf16_t* Wt, const int K, const int N, const int ntn, const int drow_off, const int gu, const int rot, ldsp lds, int tid, const int G, const int lb) {
;     ...
;   const int nn = tid & 63, kb = tid >> 6, n2 = tid >> 3, kq = tid & 7;
;   const int ktiles = K / 64, ntiles = ntn * ktiles;
;   int task = (lb + G - (rot % G)) % G;
;   float pre[8];
;   if (task < ntiles) { const int n = (task / ktiles) * 64 + nn, k0 = (task % ktiles) * 64;
; #pragma unroll
;     for (int i = 0; i < 8; ++i) pre[i] = (n < N) ? W[(size_t)(k0 + kb + 8 * i) * N + n] : 0.f; }
; DI void phase_prep(const Params& p, ldsp lds, int tid_) {
;   int tid = tid_; asm volatile("" : "+v"(tid));
;   const int G = gridDim.x, wid = tid >> 6, lane = tid & 63;
;   unsigned char* ws = p.ws;
;   tr_weight(p.in[10], (bf16_t*)(ws + W_IN), 1024, NIN, 52, 0, 0, 0, lds, tid, G, (int)blockIdx.x);
.LBB0_17:
	s_or_b64 exec, exec, s[4:5]
	s_and_b32 s99, s2, 1
	s_cmp_eq_u32 s99, 1
	s_cbranch_scc1 .LBB0_128
.Lp0_tr_entry:
	s_abs_i32 s0, s94
	v_cvt_f32_u32_e32 v0, s0
	s_sub_i32 s3, 0, s0
	s_add_i32 s1, s94, s2
	s_abs_i32 s5, s1
	v_rcp_iflag_f32_e32 v0, v0
	s_ashr_i32 s4, s1, 31
	v_mov_b32_e32 v15, v212
	v_mul_f32_e32 v0, 0x4f7ffffe, v0
	v_cvt_u32_f32_e32 v0, v0
	s_barrier
	v_readfirstlane_b32 s6, v0
	s_mul_i32 s3, s3, s6
	s_mul_hi_u32 s3, s6, s3
	s_add_i32 s3, s6, s3
	s_mul_hi_u32 s6, s5, s3
	s_mul_i32 s6, s6, s0
	s_sub_i32 s5, s5, s6
	s_sub_i32 s6, s5, s0
	s_cmp_ge_u32 s5, s0
	s_cselect_b32 s5, s6, s5
	s_sub_i32 s6, s5, s0
	s_cmp_ge_u32 s5, s0
	s_cselect_b32 s5, s6, s5
	s_xor_b32 s5, s5, s4
	s_sub_i32 s10, s5, s4
	v_ashrrev_i32_e32 v14, 6, v15
	v_and_b32_e32 v34, 63, v15
	s_cmpk_lt_i32 s10, 0x340
	v_ashrrev_i32_e32 v16, 3, v15
	s_cbranch_scc0 .LBB0_54
	s_ashr_i32 s6, s10, 31
	s_lshr_b32 s6, s6, 28
	s_load_dwordx2 s[4:5], s[72:73], 0x50
	s_add_i32 s6, s10, s6
	s_lshl_b32 s7, s6, 2
	s_andn2_b32 s7, s7, 63
	v_or_b32_e32 v0, s7, v34
	s_and_b32 s6, s6, 0x3fffff0
	s_sub_i32 s6, s10, s6
	s_movk_i32 s7, 0xc18
	v_ashrrev_i32_e32 v1, 31, v0
	v_cmp_gt_i32_e32 vcc, s7, v0
	v_lshl_add_u32 v10, s6, 6, v14
	s_waitcnt lgkmcnt(0)
	v_lshl_add_u64 v[8:9], v[0:1], 2, s[4:5]
	v_mov_b32_e32 v1, 0
	v_mov_b32_e32 v0, 0
	s_and_saveexec_b64 s[6:7], vcc
	s_cbranch_execz .LBB0_20
	s_movk_i32 s8, 0x3060
	v_mad_i64_i32 v[2:3], s[8:9], v10, s8, v[8:9]
	global_load_dword v0, v[2:3], off nt

; DI void phase_prep(const Params& p, ldsp lds, int tid_) {
;     ...
;   tr_weight(p.in[10], (bf16_t*)(ws + W_IN), 1024, NIN, 52, 0, 0, 0, lds, tid, G, (int)blockIdx.x);
;   tr_weight(p.in[25], (bf16_t*)(ws + W_KV), 1024, 1024, 16, 0, 0, 832, lds, tid, G, (int)blockIdx.x);
;   tr_weight(p.in[26], (bf16_t*)(ws + W_KV), 1024, 1024, 16, 1024, 0, 1088, lds, tid, G, (int)blockIdx.x);
;   {
.Lp0_tr_done:
	s_cmp_eq_u32 s99, 2
	s_cbranch_scc1 .Lp0n_fin

; DI void phase_prep(const Params& p, ldsp lds, int tid_) {
;     ...
;     for (int r = wv; r < NR; r += nwv) {
;       const int rn = r + 2 * nwv; f32x4 v2[4];
;       const int rc = rn < NR ? rn : r;
; #pragma unroll
;       for (int i = 0; i < 4; ++i) v2[i] = *(const f32x4*)(prep_row_src(p, rc) + RCOL(i));
;       if (r < T) rownorm_store(v0, p.in[8], (bf16_t*)(ws + B_XA) + (size_t)r * D, lane);
;       else rownorm_store(v0, p.in[23], (bf16_t*)(ws + B_MN) + (size_t)(r - T) * D, lane);
; #pragma unroll
;       for (int i = 0; i < 4; ++i) { v0[i] = v1[i]; v1[i] = v2[i]; }
;     }
;   }
; }
.Lp0n_done:
	s_cmp_eq_u32 s99, 1
	s_cbranch_scc0 .Lp0n_fin
	s_mov_b32 s99, 2
	s_branch .Lp0_tr_entry

; __global__ void __launch_bounds__(512, 2) fwd_mega(Params p) {
;   extern __shared__ __attribute__((aligned(16))) unsigned char lds_raw[];
;   ldsp lds = (ldsp)lds_raw;
;   cg::grid_group grid = cg::this_grid();
;   const int tid = threadIdx.x, G = gridDim.x, bid = blockIdx.x;
	.amdhsa_kernel _Z8fwd_mega6Params
		.amdhsa_group_segment_fixed_size 16
		.amdhsa_private_segment_fixed_size 0
		.amdhsa_kernarg_size 536
		.amdhsa_user_sgpr_count 2
		.amdhsa_user_sgpr_dispatch_ptr 0
		.amdhsa_user_sgpr_queue_ptr 0
		.amdhsa_user_sgpr_kernarg_segment_ptr 1
		.amdhsa_user_sgpr_dispatch_id 0
		.amdhsa_user_sgpr_kernarg_preload_length 0
		.amdhsa_user_sgpr_kernarg_preload_offset 0
		.amdhsa_user_sgpr_private_segment_size 0
		.amdhsa_uses_dynamic_stack 0
		.amdhsa_enable_private_segment 0
		.amdhsa_system_sgpr_workgroup_id_x 1
		.amdhsa_system_sgpr_workgroup_id_y 0
		.amdhsa_system_sgpr_workgroup_id_z 0
		.amdhsa_system_sgpr_workgroup_info 0
		.amdhsa_system_vgpr_workitem_id 2
		.amdhsa_next_free_vgpr 256
		.amdhsa_next_free_sgpr 102
		.amdhsa_accum_offset 256
		.amdhsa_reserve_vcc 1
		.amdhsa_float_round_mode_32 0
		.amdhsa_float_round_mode_16_64 0
		.amdhsa_float_denorm_mode_32 3
		.amdhsa_float_denorm_mode_16_64 3
		.amdhsa_dx10_clamp 1
		.amdhsa_ieee_mode 1
		.amdhsa_fp16_overflow 0
		.amdhsa_tg_split 0
		.amdhsa_exception_fp_ieee_invalid_op 0
		.amdhsa_exception_fp_denorm_src 0
		.amdhsa_exception_fp_ieee_div_zero 0
		.amdhsa_exception_fp_ieee_overflow 0
		.amdhsa_exception_fp_ieee_underflow 0
		.amdhsa_exception_fp_ieee_inexact 0
		.amdhsa_exception_int_div_zero 0
	.end_amdhsa_kernel

; __global__ void __launch_bounds__(512, 2) fwd_mega(Params p) {
amdhsa.kernels:
  - .agpr_count:     0
    .args:
      - .offset:         0
        .size:           280
        .value_kind:     by_value
      - .offset:         280
        .size:           4
        .value_kind:     hidden_block_count_x
      - .offset:         284
        .size:           4
        .value_kind:     hidden_block_count_y
      - .offset:         288
        .size:           4
        .value_kind:     hidden_block_count_z
      - .offset:         292
        .size:           2
        .value_kind:     hidden_group_size_x
      - .offset:         294
        .size:           2
        .value_kind:     hidden_group_size_y
      - .offset:         296
        .size:           2
        .value_kind:     hidden_group_size_z
      - .offset:         298
        .size:           2
        .value_kind:     hidden_remainder_x
      - .offset:         300
        .size:           2
        .value_kind:     hidden_remainder_y
      - .offset:         302
        .size:           2
        .value_kind:     hidden_remainder_z
      - .offset:         320
        .size:           8
        .value_kind:     hidden_global_offset_x
      - .offset:         328
        .size:           8
        .value_kind:     hidden_global_offset_y
      - .offset:         336
        .size:           8
        .value_kind:     hidden_global_offset_z
      - .offset:         344
        .size:           2
        .value_kind:     hidden_grid_dims
      - .offset:         368
        .size:           8
        .value_kind:     hidden_multigrid_sync_arg
      - .offset:         400
        .size:           4
        .value_kind:     hidden_dynamic_lds_size
    .group_segment_fixed_size: 16
    .kernarg_segment_align: 8
    .kernarg_segment_size: 536
    .language:       OpenCL C
    .language_version:
      - 2
      - 0
    .max_flat_workgroup_size: 512
    .name:           _Z8fwd_mega6Params
    .private_segment_fixed_size: 0
    .sgpr_count:     108
    .sgpr_spill_count: 24
    .symbol:         _Z8fwd_mega6Params.kd
    .uniform_work_group_size: 1
    .uses_dynamic_stack: false
    .vgpr_count:     256
    .vgpr_spill_count: 0
    .wavefront_size: 64
